# attention loop: priority raised for the softmax + PV tail of a tile, dropped for K/V staging and prefetch address math
# speedup vs baseline: 1.0006x; 1.0006x over previous
.LBB0_376:
	s_setprio 0
	s_or_b64 exec, exec, s[40:41]
	v_or_b32_e32 v122, v122, v130
	v_lshlrev_b64 v[34:35], 1, v[122:123]
	v_or_b32_e32 v34, 0x400, v34
	v_lshl_add_u64 v[36:37], v[114:115], 0, v[34:35]
	global_load_dwordx2 v[38:39], v[36:37], off
	global_load_dwordx2 v[40:41], v[36:37], off offset:16
	global_load_dwordx2 v[42:43], v[36:37], off offset:32
	global_load_dwordx2 v[44:45], v[36:37], off offset:48
	global_load_dwordx2 v[46:47], v[36:37], off offset:64
	global_load_dwordx2 v[50:51], v[36:37], off offset:80
	ds_bpermute_b32 v33, v48, v32
	global_load_dwordx2 v[48:49], v[36:37], off offset:96
	v_lshl_add_u64 v[34:35], v[116:117], 0, v[34:35]
	s_waitcnt lgkmcnt(0)
	v_add_f32_e32 v52, v32, v33
	global_load_dwordx2 v[32:33], v[36:37], off offset:112
	v_div_scale_f32 v53, s[6:7], v52, v52, 1.0
	v_rcp_f32_e32 v54, v53
	v_div_scale_f32 v36, vcc, 1.0, v52, 1.0
	v_fma_f32 v37, -v53, v54, 1.0
	v_fmac_f32_e32 v54, v37, v54
	v_mul_f32_e32 v37, v36, v54
	v_fma_f32 v55, -v53, v37, v36
	v_fmac_f32_e32 v37, v55, v54
	v_fma_f32 v36, -v53, v37, v36
	v_div_fmas_f32 v36, v36, v54, v37
	v_div_fixup_f32 v36, v36, v52, 1.0
	v_pk_mul_f32 v[16:17], v[16:17], v[36:37] op_sel_hi:[1,0]
	v_pk_mul_f32 v[18:19], v[18:19], v[36:37] op_sel_hi:[1,0]
	v_pk_mul_f32 v[0:1], v[0:1], v[36:37] op_sel_hi:[1,0]
	v_pk_mul_f32 v[2:3], v[2:3], v[36:37] op_sel_hi:[1,0]
	v_pk_mul_f32 v[20:21], v[20:21], v[36:37] op_sel_hi:[1,0]
	v_pk_mul_f32 v[22:23], v[22:23], v[36:37] op_sel_hi:[1,0]
	v_pk_mul_f32 v[24:25], v[24:25], v[36:37] op_sel_hi:[1,0]
	v_pk_mul_f32 v[26:27], v[26:27], v[36:37] op_sel_hi:[1,0]
	v_pk_mul_f32 v[28:29], v[28:29], v[36:37] op_sel_hi:[1,0]
	v_pk_mul_f32 v[30:31], v[30:31], v[36:37] op_sel_hi:[1,0]
	v_pk_mul_f32 v[4:5], v[4:5], v[36:37] op_sel_hi:[1,0]
	s_waitcnt vmcnt(7)
	v_lshlrev_b32_e32 v52, 16, v38
	v_and_b32_e32 v53, 0xffff0000, v38
	v_lshlrev_b32_e32 v38, 16, v39
	v_and_b32_e32 v39, 0xffff0000, v39
	s_waitcnt vmcnt(3)
	v_lshlrev_b32_e32 v60, 16, v46
	v_and_b32_e32 v61, 0xffff0000, v46
	v_lshlrev_b32_e32 v46, 16, v47
	v_and_b32_e32 v47, 0xffff0000, v47
	v_lshlrev_b32_e32 v54, 16, v40
	v_and_b32_e32 v55, 0xffff0000, v40
	v_lshlrev_b32_e32 v40, 16, v41
	v_and_b32_e32 v41, 0xffff0000, v41
	v_lshlrev_b32_e32 v56, 16, v42
	v_and_b32_e32 v57, 0xffff0000, v42
	v_lshlrev_b32_e32 v42, 16, v43
	v_and_b32_e32 v43, 0xffff0000, v43
	v_lshlrev_b32_e32 v58, 16, v44
	v_and_b32_e32 v59, 0xffff0000, v44
	v_lshlrev_b32_e32 v44, 16, v45
	v_and_b32_e32 v45, 0xffff0000, v45
	v_pk_mul_f32 v[16:17], v[16:17], v[52:53]
	v_pk_mul_f32 v[18:19], v[18:19], v[38:39]
	v_pk_mul_f32 v[0:1], v[0:1], v[60:61]
	v_pk_mul_f32 v[2:3], v[2:3], v[46:47]
	v_pk_mul_f32 v[20:21], v[20:21], v[54:55]
	v_pk_mul_f32 v[22:23], v[22:23], v[40:41]
	v_pk_mul_f32 v[24:25], v[24:25], v[56:57]
	v_pk_mul_f32 v[26:27], v[26:27], v[42:43]
	v_pk_mul_f32 v[28:29], v[28:29], v[58:59]
	v_pk_mul_f32 v[30:31], v[30:31], v[44:45]
	v_cvt_pk_bf16_f32 v16, v16, v17
	v_cvt_pk_bf16_f32 v17, v18, v19
	v_cvt_pk_bf16_f32 v0, v0, v1
	v_cvt_pk_bf16_f32 v1, v2, v3
	s_waitcnt vmcnt(2)
	v_lshlrev_b32_e32 v62, 16, v50
	v_and_b32_e32 v63, 0xffff0000, v50
	v_cvt_pk_bf16_f32 v18, v20, v21
	v_cvt_pk_bf16_f32 v19, v22, v23
	v_cvt_pk_bf16_f32 v20, v24, v25
	v_cvt_pk_bf16_f32 v21, v26, v27
	v_cvt_pk_bf16_f32 v22, v28, v29
	v_cvt_pk_bf16_f32 v23, v30, v31
	global_store_dwordx2 v[34:35], v[16:17], off
	global_store_dwordx2 v[34:35], v[18:19], off offset:16
	global_store_dwordx2 v[34:35], v[20:21], off offset:32
	global_store_dwordx2 v[34:35], v[22:23], off offset:48
	global_store_dwordx2 v[34:35], v[0:1], off offset:64
	v_lshlrev_b32_e32 v0, 16, v51
	v_and_b32_e32 v1, 0xffff0000, v51
	v_pk_mul_f32 v[2:3], v[6:7], v[36:37] op_sel_hi:[1,0]
	v_pk_mul_f32 v[4:5], v[4:5], v[62:63]
	v_pk_mul_f32 v[0:1], v[2:3], v[0:1]
	v_cvt_pk_bf16_f32 v2, v4, v5
	v_cvt_pk_bf16_f32 v3, v0, v1
	global_store_dwordx2 v[34:35], v[2:3], off offset:80
	s_waitcnt vmcnt(7)
	v_lshlrev_b32_e32 v0, 16, v48
	v_and_b32_e32 v1, 0xffff0000, v48
	v_pk_mul_f32 v[2:3], v[8:9], v[36:37] op_sel_hi:[1,0]
	v_pk_mul_f32 v[4:5], v[10:11], v[36:37] op_sel_hi:[1,0]
	v_pk_mul_f32 v[0:1], v[2:3], v[0:1]
	v_lshlrev_b32_e32 v2, 16, v49
	v_and_b32_e32 v3, 0xffff0000, v49
	v_pk_mul_f32 v[2:3], v[4:5], v[2:3]
	v_cvt_pk_bf16_f32 v0, v0, v1
	v_cvt_pk_bf16_f32 v1, v2, v3
	s_waitcnt vmcnt(6)
	v_and_b32_e32 v3, 0xffff0000, v32
	v_lshlrev_b32_e32 v2, 16, v32
	v_pk_mul_f32 v[4:5], v[12:13], v[36:37] op_sel_hi:[1,0]
	global_store_dwordx2 v[34:35], v[0:1], off offset:96
	v_lshlrev_b32_e32 v0, 16, v33
	v_pk_mul_f32 v[2:3], v[4:5], v[2:3]
	v_and_b32_e32 v1, 0xffff0000, v33
	v_pk_mul_f32 v[4:5], v[14:15], v[36:37] op_sel_hi:[1,0]
	v_cvt_pk_bf16_f32 v2, v2, v3
	v_pk_mul_f32 v[0:1], v[4:5], v[0:1]
	s_nop 0
	v_cvt_pk_bf16_f32 v3, v0, v1
	global_store_dwordx2 v[34:35], v[2:3], off offset:112

.LBB0_392:
	s_setprio 1
	s_or_b64 exec, exec, s[44:45]
	s_nop 8
	v_max_f32_e32 v48, v33, v33
	v_max_f32_e32 v49, v32, v32
	v_max_f32_e32 v48, v49, v48
	v_max3_f32 v48, v48, v34, v35
	v_max3_f32 v48, v48, v36, v37
	v_max3_f32 v48, v48, v38, v39
	v_max3_f32 v48, v48, v40, v41
	v_max3_f32 v48, v48, v42, v43
	v_max3_f32 v48, v48, v44, v45
	v_and_b32_e32 v50, 64, v149
	v_max3_f32 v49, v48, v46, v47
	v_xor_b32_e32 v48, 32, v149
	v_add_u32_e32 v50, 64, v50
	v_cmp_lt_i32_e32 vcc, v48, v50
	v_add_u32_e32 v63, 0x1000, v146
	s_add_i32 s63, s63, 32
	v_cndmask_b32_e32 v48, v149, v48, vcc
	v_lshlrev_b32_e32 v48, 2, v48
	ds_bpermute_b32 v50, v48, v49
	v_cmp_eq_u32_e32 vcc, s64, v150
	v_lshl_add_u64 v[138:139], v[138:139], 0, s[38:39]
	s_or_b64 s[40:41], vcc, s[40:41]
	s_mov_b32 s65, s64
	s_waitcnt lgkmcnt(0)
	v_max3_f32 v49, v156, v49, v50
	v_sub_f32_e32 v32, v32, v49
	v_exp_f32_e32 v50, v32
	v_sub_f32_e32 v32, v33, v49
	v_exp_f32_e32 v51, v32
	v_sub_f32_e32 v34, v34, v49
	v_exp_f32_e32 v52, v34
	v_sub_f32_e32 v34, v35, v49
	v_exp_f32_e32 v53, v34
	v_sub_f32_e32 v34, v36, v49
	v_add_f32_e32 v33, 0, v50
	v_exp_f32_e32 v54, v34
	v_sub_f32_e32 v34, v37, v49
	v_add_f32_e32 v33, v51, v33
	v_exp_f32_e32 v55, v34
	v_sub_f32_e32 v34, v38, v49
	v_add_f32_e32 v33, v52, v33
	v_exp_f32_e32 v56, v34
	v_sub_f32_e32 v34, v39, v49
	v_add_f32_e32 v33, v53, v33
	v_exp_f32_e32 v39, v34
	v_sub_f32_e32 v34, v40, v49
	v_add_f32_e32 v33, v54, v33
	v_exp_f32_e32 v57, v34
	v_sub_f32_e32 v34, v41, v49
	v_add_f32_e32 v33, v55, v33
	v_exp_f32_e32 v58, v34
	v_add_f32_e32 v33, v56, v33
	v_add_f32_e32 v33, v39, v33
	v_add_f32_e32 v33, v57, v33
	v_add_f32_e32 v59, v58, v33
	v_sub_f32_e32 v33, v42, v49
	v_exp_f32_e32 v60, v33
	v_sub_f32_e32 v33, v43, v49
	v_sub_f32_e32 v32, v156, v49
	v_exp_f32_e32 v61, v33
	v_sub_f32_e32 v33, v44, v49
	v_exp_f32_e32 v62, v33
	v_sub_f32_e32 v33, v45, v49
	v_exp_f32_e32 v44, v32
	v_sub_f32_e32 v32, v46, v49
	v_cvt_pk_bf16_f32 v36, v50, v51
	v_add_u32_e32 v50, 0x1800, v146
	v_exp_f32_e32 v45, v33
	v_exp_f32_e32 v46, v32
	ds_read2_b64 v[32:35], v63 offset0:64 offset1:66
	ds_read2_b64 v[40:43], v50 offset0:128 offset1:130
	v_pk_mul_f32 v[30:31], v[30:31], v[44:45] op_sel_hi:[1,0]
	v_pk_mul_f32 v[28:29], v[28:29], v[44:45] op_sel_hi:[1,0]
	v_pk_mul_f32 v[26:27], v[26:27], v[44:45] op_sel_hi:[1,0]
	v_pk_mul_f32 v[24:25], v[24:25], v[44:45] op_sel_hi:[1,0]
	v_pk_mul_f32 v[22:23], v[22:23], v[44:45] op_sel_hi:[1,0]
	v_pk_mul_f32 v[20:21], v[20:21], v[44:45] op_sel_hi:[1,0]
	v_pk_mul_f32 v[18:19], v[18:19], v[44:45] op_sel_hi:[1,0]
	v_pk_mul_f32 v[16:17], v[16:17], v[44:45] op_sel_hi:[1,0]
	v_pk_mul_f32 v[14:15], v[14:15], v[44:45] op_sel_hi:[1,0]
	v_pk_mul_f32 v[12:13], v[12:13], v[44:45] op_sel_hi:[1,0]
	v_cvt_pk_bf16_f32 v37, v52, v53
	v_cvt_pk_bf16_f32 v38, v54, v55
	v_cvt_pk_bf16_f32 v39, v56, v39
	v_pk_mul_f32 v[10:11], v[10:11], v[44:45] op_sel_hi:[1,0]
	v_pk_mul_f32 v[8:9], v[8:9], v[44:45] op_sel_hi:[1,0]
	v_pk_mul_f32 v[6:7], v[6:7], v[44:45] op_sel_hi:[1,0]
	v_pk_mul_f32 v[4:5], v[4:5], v[44:45] op_sel_hi:[1,0]
	v_pk_mul_f32 v[2:3], v[2:3], v[44:45] op_sel_hi:[1,0]
	v_pk_mul_f32 v[0:1], v[0:1], v[44:45] op_sel_hi:[1,0]
	s_waitcnt lgkmcnt(1)
	v_mfma_f32_32x32x16_bf16 v[16:31], v[32:35], v[36:39], v[16:31]
	ds_read2_b64 v[32:35], v63 offset0:68 offset1:70
	v_mov_b32_e32 v156, v49
	s_waitcnt lgkmcnt(1)
	v_mfma_f32_32x32x16_bf16 v[0:15], v[40:43], v[36:39], v[0:15]
	ds_read2_b64 v[40:43], v50 offset0:132 offset1:134
	v_sub_f32_e32 v36, v47, v49
	v_exp_f32_e32 v47, v36
	v_cvt_pk_bf16_f32 v36, v57, v58
	v_cvt_pk_bf16_f32 v37, v60, v61
	v_cvt_pk_bf16_f32 v38, v62, v45
	v_cvt_pk_bf16_f32 v39, v46, v47
	s_waitcnt lgkmcnt(1)
	s_nop 0
	v_mfma_f32_32x32x16_bf16 v[16:31], v[32:35], v[36:39], v[16:31]
	v_add_f32_e32 v32, v60, v59
	v_add_f32_e32 v32, v61, v32
	v_add_f32_e32 v32, v62, v32
	v_add_f32_e32 v32, v45, v32
	v_add_f32_e32 v32, v46, v32
	v_add_f32_e32 v32, v47, v32
	v_fmac_f32_e32 v32, v155, v44
	s_waitcnt lgkmcnt(0)
	v_mfma_f32_32x32x16_bf16 v[0:15], v[40:43], v[36:39], v[0:15]
	v_mov_b32_e32 v155, v32
	s_andn2_b64 exec, exec, s[40:41]
	s_cbranch_execz .LBB0_376
.LBB0_393:
	s_setprio 0
	s_add_i32 s64, s65, 1
	s_waitcnt vmcnt(7)
	ds_write_b128 v220, v[80:83]
	s_waitcnt vmcnt(6)
	ds_write_b128 v221, v[84:87] offset:4608
	s_waitcnt vmcnt(5)
	ds_write_b128 v220, v[88:91] offset:1152
	s_waitcnt vmcnt(4)
	ds_write_b128 v221, v[92:95] offset:5888
	s_waitcnt vmcnt(3)
	ds_write_b128 v220, v[96:99] offset:2304
	s_waitcnt vmcnt(2)
	ds_write_b128 v221, v[100:103] offset:7168
	s_waitcnt vmcnt(1)
	ds_write_b128 v220, v[104:107] offset:3456
	v_cmp_lt_u32_e32 vcc, s64, v150
	s_waitcnt vmcnt(0)
	ds_write_b128 v221, v[108:111] offset:8448
	ds_read_b128 v[158:161], v147
	ds_read_b128 v[162:165], v147 offset:32
	ds_read_b128 v[166:169], v147 offset:64
	ds_read_b128 v[170:173], v147 offset:96
	s_and_saveexec_b64 s[8:9], vcc
	s_cbranch_execz .LBB0_401
	v_mov_b32_e32 v38, v131
	v_mov_b64_e32 v[32:33], 0x100
	v_mov_b32_e32 v112, s63
	v_mov_b64_e32 v[36:37], v[128:129]
	v_mov_b64_e32 v[34:35], v[138:139]
	s_and_saveexec_b64 s[44:45], s[6:7]
	s_cbranch_execz .LBB0_400
	s_cmp_gt_u32 s65, 14
	s_mov_b64 s[46:47], -1
	s_cbranch_scc0 .LBB0_397
	s_add_i32 s36, s65, -15
	s_lshr_b32 s36, s36, 1
	v_add_u32_e32 v36, s36, v119
	s_and_b32 s66, s63, 32
	v_lshl_or_b32 v112, v36, 6, s66
	v_lshlrev_b64 v[32:33], 10, v[112:113]
	v_lshlrev_b32_e32 v112, 7, v36
	v_lshl_add_u64 v[34:35], v[134:135], 0, v[32:33]
	v_lshl_add_u64 v[36:37], v[136:137], 0, v[112:113]
	s_mov_b64 s[46:47], 0
